# v8 + nt (streaming) policy on the pass1/pass2 raw projection-row loads
# baseline (speedup 1.0000x reference)
.LBB0_1150:
	s_ashr_i32 s0, s2, 6
	v_mov_b32_e32 v180, 0
	v_mov_b32_e32 v181, 0
	v_mov_b32_e32 v182, 0
	v_mov_b32_e32 v183, 0
	v_mov_b32_e32 v184, 0
	v_mov_b32_e32 v185, 0
	v_mov_b32_e32 v186, 0
	v_mov_b32_e32 v187, 0
	s_ashr_i32 s1, s0, 31
	s_lshl_b32 s3, s2, 8
	s_lshl_b64 s[0:1], s[0:1], 12
	s_and_b32 s3, s3, 0xf00
	s_or_b32 s4, s0, s3
	s_mov_b32 s5, s1
	v_lshl_add_u64 v[8:9], s[4:5], 0, v[54:55]
	v_mov_b64_e32 v[10:11], s[52:53]
	s_movk_i32 s6, 0x1600
	v_mad_u64_u32 v[10:11], s[4:5], v8, s6, v[10:11]
	s_lshl_b32 s3, s2, 4
	v_mad_i32_i24 v11, v9, s6, v11
	s_and_b32 s54, s3, 0x300
	v_lshl_add_u64 v[8:9], v[10:11], 0, s[54:55]
	v_mov_b32_e32 v61, v16
	v_lshl_add_u64 v[8:9], v[8:9], 0, v[60:61]
	global_load_dwordx4 v[42:45], v[8:9], off offset:2560 nt
	global_load_dwordx4 v[46:49], v[8:9], off offset:3584 nt
	s_lshl_b32 s4, s8, 1
	s_and_b32 s4, s4, 0x300
	v_mov_b32_e32 v8, s4
	v_readfirstlane_b32 s4, v17
	s_ashr_i32 s5, s4, 6
	s_lshl_b32 s4, s5, 4
	v_or_b32_e32 v10, s4, v64
	s_and_b32 s3, s9, 0xf00
	v_lshlrev_b32_e32 v12, 1, v10
	v_or_b32_e32 v10, s4, v56
	v_lshlrev_b32_e32 v74, 1, v10
	v_or_b32_e32 v10, s4, v67
	s_or_b32 s0, s0, s3
	v_mov_b32_e32 v9, v16
	v_lshlrev_b32_e32 v13, 1, v10
	v_lshl_add_u64 v[10:11], s[0:1], 0, v[54:55]
	v_mad_u64_u32 v[8:9], s[0:1], v10, s6, v[8:9]
	v_mad_i32_i24 v9, v11, s6, v9
	v_mov_b32_e32 v61, 0
	v_add_u32_e32 v76, 0, v74
	v_lshl_add_u64 v[62:63], v[58:59], 0, v[8:9]
	s_mov_b64 s[6:7], 0
	v_add_u32_e32 v78, v65, v12
	v_add_u32_e32 v73, v66, v13
	v_mov_b32_e32 v8, 0
	v_mov_b32_e32 v9, v61
	v_mov_b32_e32 v10, v61
	v_mov_b32_e32 v11, v61
	v_mov_b32_e32 v12, 0
	v_mov_b32_e32 v13, v61
	v_mov_b32_e32 v14, v61
	v_mov_b32_e32 v15, v61
	v_mov_b32_e32 v18, 0
	v_mov_b32_e32 v19, v61
	v_mov_b32_e32 v20, v61
	v_mov_b32_e32 v21, v61
	v_mov_b32_e32 v22, 0
	v_mov_b32_e32 v23, v61
	v_mov_b32_e32 v24, v61
	v_mov_b32_e32 v25, v61
	v_mov_b32_e32 v26, 0
	v_mov_b32_e32 v27, v61
	v_mov_b32_e32 v28, v61
	v_mov_b32_e32 v29, v61
	v_mov_b32_e32 v30, 0
	v_mov_b32_e32 v31, v61
	v_mov_b32_e32 v32, v61
	v_mov_b32_e32 v33, v61
	v_mov_b32_e32 v34, 0
	v_mov_b32_e32 v35, v61
	v_mov_b32_e32 v36, v61
	v_mov_b32_e32 v37, v61
	v_mov_b32_e32 v38, 0
	v_mov_b32_e32 v39, v61
	v_mov_b32_e32 v40, v61
	v_mov_b32_e32 v41, v61
	v_add_u32_e32 v77, v76, v69
	s_branch .LBB0_1152

.LBB0_1152:
	s_waitcnt vmcnt(1)
	ds_write_b128 v70, v[42:45] offset:17408
	s_waitcnt vmcnt(0)
	ds_write_b128 v70, v[46:49] offset:37888
	v_lshl_add_u64 v[42:43], v[62:63], 0, s[6:7]
	s_mov_b32 s0, 0x6b2c000
	v_add_co_u32_e64 v46, s[0:1], s0, v42
	v_and_or_b32 v50, v221, 64, v56
	s_nop 0
	v_addc_co_u32_e64 v47, s[0:1], 0, v43, s[0:1]
	global_load_dwordx4 v[42:45], v[46:47], off offset:2560 nt
	s_nop 0
	global_load_dwordx4 v[46:49], v[46:47], off offset:3584 nt
	s_waitcnt lgkmcnt(0)
	s_barrier
	ds_read_b64_tr_b16 v[80:81], v78 offset:17408
	ds_read_b64_tr_b16 v[82:83], v78 offset:18688
	ds_read_u16_d16_hi v180, v77 offset:17408
	ds_read_u16_d16_hi v181, v77 offset:17728
	ds_read_u16_d16_hi v182, v77 offset:18048
	ds_read_u16_d16_hi v183, v77 offset:18368
	ds_read_u16_d16_hi v184, v77 offset:22528
	ds_read_u16_d16_hi v185, v77 offset:22848
	ds_read_u16_d16_hi v186, v77 offset:23168
	ds_read_u16_d16_hi v187, v77 offset:23488
	s_waitcnt lgkmcnt(8)
	v_mfma_f32_16x16x32_bf16 v[84:87], v[0:3], v[80:83], 0
	v_lshlrev_b32_e32 v79, 2, v50
	v_mfma_f32_16x16x32_bf16 v[80:83], v[4:7], v[80:83], 0
	s_nop 5
	ds_bpermute_b32 v50, v79, v87 offset:192
	s_waitcnt lgkmcnt(0)
	v_exp_f32_e32 v188, v180
	v_exp_f32_e32 v189, v181
	v_exp_f32_e32 v190, v182
	v_exp_f32_e32 v191, v183
	v_exp_f32_e32 v192, v184
	v_exp_f32_e32 v193, v185
	v_exp_f32_e32 v194, v186
	v_exp_f32_e32 v195, v187
	v_sub_f32_e32 v196, v50, v80
	v_sub_f32_e32 v197, v50, v81
	v_sub_f32_e32 v198, v50, v82
	v_sub_f32_e32 v199, v50, v83
	v_sub_f32_e32 v200, v50, v84
	v_sub_f32_e32 v201, v50, v85
	v_sub_f32_e32 v202, v50, v86
	v_sub_f32_e32 v203, v50, v87
	v_exp_f32_e32 v196, v196
	v_exp_f32_e32 v197, v197
	v_exp_f32_e32 v198, v198
	v_exp_f32_e32 v199, v199
	v_exp_f32_e32 v200, v200
	v_exp_f32_e32 v201, v201
	v_exp_f32_e32 v202, v202
	v_exp_f32_e32 v203, v203
	v_sub_f32_e32 v188, 1.0, v188
	v_sub_f32_e32 v189, 1.0, v189
	v_sub_f32_e32 v190, 1.0, v190
	v_sub_f32_e32 v191, 1.0, v191
	v_sub_f32_e32 v192, 1.0, v192
	v_sub_f32_e32 v193, 1.0, v193
	v_sub_f32_e32 v194, 1.0, v194
	v_sub_f32_e32 v195, 1.0, v195
	v_mul_f32_e32 v196, v196, v188
	v_mul_f32_e32 v197, v197, v189
	v_mul_f32_e32 v198, v198, v190
	v_mul_f32_e32 v199, v199, v191
	v_mul_f32_e32 v200, v200, v192
	v_mul_f32_e32 v201, v201, v193
	v_mul_f32_e32 v202, v202, v194
	v_mul_f32_e32 v203, v203, v195
	v_cvt_pk_bf16_f32 v204, v196, v197
	v_cvt_pk_bf16_f32 v205, v198, v199
	v_cvt_pk_bf16_f32 v206, v200, v201
	v_cvt_pk_bf16_f32 v207, v202, v203
	ds_write_b16 v77, v204 offset:27648
	ds_write_b16_d16_hi v77, v204 offset:27968
	ds_write_b16 v77, v205 offset:28288
	ds_write_b16_d16_hi v77, v205 offset:28608
	ds_write_b16 v77, v206 offset:32768
	ds_write_b16_d16_hi v77, v206 offset:33088
	ds_write_b16 v77, v207 offset:33408
	ds_write_b16_d16_hi v77, v207 offset:33728
	s_and_saveexec_b64 s[0:1], vcc
	s_cbranch_execz .LBB0_1151
	v_exp_f32_e32 v51, v50
	v_add_u32_e32 v52, v76, v74
	ds_write_b32 v52, v51 offset:56832
	s_branch .LBB0_1151

.LBB0_1326:
	v_readfirstlane_b32 s19, v17
	s_ashr_i32 s20, s18, 6
	s_ashr_i32 s26, s19, 6
	s_ashr_i32 s21, s20, 31
	s_lshl_b32 s19, s18, 8
	s_lshl_b64 s[20:21], s[20:21], 12
	s_and_b32 s19, s19, 0xf00
	s_or_b32 s22, s20, s19
	s_mov_b32 s23, s21
	s_waitcnt vmcnt(4)
	v_lshl_add_u64 v[8:9], s[22:23], 0, v[74:75]
	v_mov_b64_e32 v[10:11], s[52:53]
	s_movk_i32 s19, 0x1600
	v_mad_u64_u32 v[10:11], s[22:23], v8, s19, v[10:11]
	v_mad_i32_i24 v11, v9, s19, v11
	s_lshl_b32 s19, s18, 4
	s_and_b32 s54, s19, 0x300
	v_lshl_add_u64 v[8:9], v[10:11], 0, s[54:55]
	v_mov_b32_e32 v87, v16
	v_lshl_add_u64 v[26:27], v[8:9], 0, v[86:87]
	global_load_dwordx4 v[8:11], v[26:27], off offset:1536 nt
	global_load_dwordx4 v[12:15], v[26:27], off offset:2560 nt
	global_load_dwordx4 v[18:21], v[26:27], off offset:3584 nt
	s_waitcnt vmcnt(4)
	v_add_co_u32_e32 v22, vcc, s68, v26
	s_ashr_i32 s19, s18, 31
	s_nop 0
	v_addc_co_u32_e32 v23, vcc, 0, v27, vcc
	global_load_dwordx4 v[22:25], v[22:23], off offset:512 nt
	s_lshl_b64 s[22:23], s[18:19], 15
	s_add_u32 s22, s62, s22
	s_addc_u32 s23, s63, s23
	v_lshl_or_b32 v28, s26, 11, v92
	s_lshl_b32 s27, s26, 4
	v_ashrrev_i32_e32 v29, 31, v28
	v_or_b32_e32 v42, s27, v95
	v_lshl_add_u64 v[28:29], v[28:29], 1, s[22:23]
	v_ashrrev_i32_e32 v43, 31, v42
	global_load_dwordx2 v[38:39], v[28:29], off
	global_load_dwordx2 v[34:35], v[28:29], off offset:512
	global_load_dwordx2 v[36:37], v[28:29], off offset:1024
	global_load_dwordx2 v[40:41], v[28:29], off offset:1536
	global_load_dwordx2 v[44:45], v[28:29], off offset:2048
	global_load_dwordx2 v[48:49], v[28:29], off offset:2560
	global_load_dwordx2 v[52:53], v[28:29], off offset:3072
	global_load_dwordx2 v[56:57], v[28:29], off offset:3584
	v_lshl_add_u64 v[28:29], v[42:43], 2, s[70:71]
	global_load_dword v87, v[28:29], off
	v_add_u32_e32 v28, v76, v80
	s_mov_b32 s19, 0x2d000
	v_lshlrev_b32_e32 v122, 1, v42
	v_and_or_b32 v43, v221, 64, v77
	v_mov_b32_e32 v46, 0xc0
	v_add_u32_e32 v42, 0, v122
	v_lshl_or_b32 v121, v43, 2, v46
	v_add_u32_e32 v46, v42, v98
	s_waitcnt vmcnt(12)
	ds_write_b128 v28, v[8:11]
	v_add_u32_e32 v8, v78, v80
	s_waitcnt vmcnt(11)
	ds_write_b128 v8, v[12:15] offset:17408
	s_waitcnt vmcnt(10)
	ds_write_b128 v8, v[18:21] offset:37888
	s_waitcnt vmcnt(9)
	ds_write_b128 v81, v[22:25] offset:48128
	v_add_co_u32_e32 v18, vcc, s44, v26
	s_nop 1
	v_addc_co_u32_e32 v19, vcc, 0, v27, vcc
	v_add_co_u32_e32 v22, vcc, s19, v26
	v_or_b32_e32 v26, s27, v79
	s_nop 0
	v_addc_co_u32_e32 v23, vcc, 0, v27, vcc
	v_lshlrev_b32_e32 v120, 1, v26
	global_load_dwordx4 v[8:11], v[18:19], off offset:1536
	global_load_dwordx4 v[12:15], v[18:19], off offset:2560 nt
	s_nop 0
	global_load_dwordx4 v[18:21], v[18:19], off offset:3584 nt
	v_add_u32_e32 v28, v97, v120
	global_load_dwordx4 v[22:25], v[22:23], off offset:512 nt
	s_waitcnt lgkmcnt(0)
	s_barrier
	ds_read_b64_tr_b16 v[26:27], v28 offset:17408
	ds_read_b64_tr_b16 v[28:29], v28 offset:18688
	ds_read_u16 v47, v46 offset:17408
	s_waitcnt lgkmcnt(1)
	v_mfma_f32_16x16x32_bf16 v[30:33], v[4:7], v[26:29], 0
	s_waitcnt lgkmcnt(0)
	v_lshlrev_b32_e32 v50, 16, v47
	v_add_u32_e32 v47, v42, v99
	ds_read_u16 v51, v47
	v_mfma_f32_16x16x32_bf16 v[26:29], v[0:3], v[26:29], 0
	s_nop 2
	v_exp_f32_e32 v54, v30
	v_exp_f32_e32 v50, v50
	s_waitcnt lgkmcnt(0)
	v_lshlrev_b32_e32 v51, 16, v51
	v_mul_f32_e32 v51, v54, v51
	ds_bpermute_b32 v43, v121, v29
	v_cvt_pk_bf16_f32 v51, v51, v51
	ds_write_b16 v47, v51
	v_max_f32_e64 v51, -v30, -v30
	v_min_f32_e32 v51, 0x42e60000, v51
	s_waitcnt lgkmcnt(1)
	v_sub_f32_e32 v30, v43, v30
	v_exp_f32_e32 v51, v51
	v_exp_f32_e32 v30, v30
	v_sub_f32_e32 v50, 1.0, v50
	v_mul_f32_e32 v51, v51, v50
	v_mul_f32_e32 v30, v30, v50
	v_cvt_pk_bf16_f32 v51, v51, v51
	ds_write_b16 v47, v51 offset:8704
	v_cvt_pk_bf16_f32 v30, v30, v30
	ds_write_b16 v46, v30 offset:27648
	ds_read_u16 v30, v46 offset:17728
	ds_read_u16 v50, v47 offset:272
	v_exp_f32_e32 v51, v31
	s_waitcnt lgkmcnt(1)
	v_lshlrev_b32_e32 v30, 16, v30
	s_waitcnt lgkmcnt(0)
	v_lshlrev_b32_e32 v50, 16, v50
	v_mul_f32_e32 v50, v51, v50
	v_cvt_pk_bf16_f32 v50, v50, v50
	ds_write_b16 v47, v50 offset:272
	v_max_f32_e64 v50, -v31, -v31
	v_exp_f32_e32 v30, v30
	v_min_f32_e32 v50, 0x42e60000, v50
	v_sub_f32_e32 v31, v43, v31
	v_exp_f32_e32 v50, v50
	v_exp_f32_e32 v31, v31
	v_sub_f32_e32 v30, 1.0, v30
	v_exp_f32_e32 v51, v33
	v_mul_f32_e32 v50, v50, v30
	v_mul_f32_e32 v30, v31, v30
	v_cvt_pk_bf16_f32 v50, v50, v50
	ds_write_b16 v47, v50 offset:8976
	v_cvt_pk_bf16_f32 v30, v30, v30
	ds_write_b16 v46, v30 offset:27968
	ds_read_u16 v30, v46 offset:18048
	ds_read_u16 v31, v47 offset:544
	v_exp_f32_e32 v50, v32
	s_waitcnt lgkmcnt(1)
	v_lshlrev_b32_e32 v30, 16, v30
	s_waitcnt lgkmcnt(0)
	v_lshlrev_b32_e32 v31, 16, v31
	v_mul_f32_e32 v31, v50, v31
	v_cvt_pk_bf16_f32 v31, v31, v31
	ds_write_b16 v47, v31 offset:544
	v_max_f32_e64 v31, -v32, -v32
	v_exp_f32_e32 v30, v30
	v_min_f32_e32 v31, 0x42e60000, v31
	v_exp_f32_e32 v31, v31
	v_sub_f32_e32 v30, 1.0, v30
	v_mul_f32_e32 v31, v31, v30
	v_cvt_pk_bf16_f32 v31, v31, v31
	ds_write_b16 v47, v31 offset:9248
	v_sub_f32_e32 v31, v43, v32
	v_exp_f32_e32 v31, v31
	v_add_u32_e32 v32, v42, v101
	v_mul_f32_e32 v30, v31, v30
	v_cvt_pk_bf16_f32 v30, v30, v30
	ds_write_b16 v46, v30 offset:28288
	v_add_u32_e32 v30, v42, v100
	ds_read_u16 v31, v30 offset:17408
	ds_read_u16 v50, v32
	s_waitcnt lgkmcnt(1)
	v_lshlrev_b32_e32 v31, 16, v31
	s_waitcnt lgkmcnt(0)
	v_lshlrev_b32_e32 v50, 16, v50
	v_mul_f32_e32 v50, v51, v50
	v_cvt_pk_bf16_f32 v50, v50, v50
	ds_write_b16 v32, v50
	v_max_f32_e64 v50, -v33, -v33
	v_exp_f32_e32 v31, v31
	v_min_f32_e32 v50, 0x42e60000, v50
	v_exp_f32_e32 v50, v50
	v_sub_f32_e32 v31, 1.0, v31
	v_mul_f32_e32 v50, v50, v31
	v_cvt_pk_bf16_f32 v50, v50, v50
	ds_write_b16 v32, v50 offset:8704
	v_sub_f32_e32 v32, v43, v33
	v_exp_f32_e32 v32, v32
	s_nop 0
	v_mul_f32_e32 v31, v32, v31
	v_cvt_pk_bf16_f32 v31, v31, v31
	ds_write_b16 v30, v31 offset:27648
	ds_read_u16 v30, v46 offset:22528
	ds_read_u16 v31, v47 offset:4352
	v_exp_f32_e32 v32, v26
	s_waitcnt lgkmcnt(1)
	v_lshlrev_b32_e32 v30, 16, v30
	s_waitcnt lgkmcnt(0)
	v_lshlrev_b32_e32 v31, 16, v31
	v_mul_f32_e32 v31, v32, v31
	v_cvt_pk_bf16_f32 v31, v31, v31
	ds_write_b16 v47, v31 offset:4352
	v_max_f32_e64 v31, -v26, -v26
	v_exp_f32_e32 v30, v30
	v_min_f32_e32 v31, 0x42e60000, v31
	v_sub_f32_e32 v26, v43, v26
	v_exp_f32_e32 v31, v31
	v_exp_f32_e32 v26, v26
	v_sub_f32_e32 v30, 1.0, v30
	v_mul_f32_e32 v31, v31, v30
	v_mul_f32_e32 v26, v26, v30
	v_cvt_pk_bf16_f32 v31, v31, v31
	ds_write_b16 v47, v31 offset:13056
	v_cvt_pk_bf16_f32 v26, v26, v26
	ds_write_b16 v46, v26 offset:32768
	ds_read_u16 v26, v46 offset:22848
	ds_read_u16 v30, v47 offset:4624
	v_exp_f32_e32 v31, v27
	s_waitcnt lgkmcnt(1)
	v_lshlrev_b32_e32 v26, 16, v26
	s_waitcnt lgkmcnt(0)
	v_lshlrev_b32_e32 v30, 16, v30
	v_mul_f32_e32 v30, v31, v30
	v_cvt_pk_bf16_f32 v30, v30, v30
	ds_write_b16 v47, v30 offset:4624
	v_max_f32_e64 v30, -v27, -v27
	v_exp_f32_e32 v26, v26
	v_min_f32_e32 v30, 0x42e60000, v30
	v_sub_f32_e32 v27, v43, v27
	v_exp_f32_e32 v30, v30
	v_exp_f32_e32 v27, v27
	v_sub_f32_e32 v26, 1.0, v26
	v_exp_f32_e32 v31, v29
	v_mul_f32_e32 v30, v30, v26
	v_mul_f32_e32 v26, v27, v26
	v_cvt_pk_bf16_f32 v30, v30, v30
	ds_write_b16 v47, v30 offset:13328
	v_cvt_pk_bf16_f32 v26, v26, v26
	ds_write_b16 v46, v26 offset:33088
	ds_read_u16 v26, v46 offset:23168
	ds_read_u16 v27, v47 offset:4896
	v_exp_f32_e32 v30, v28
	s_waitcnt lgkmcnt(1)
	v_lshlrev_b32_e32 v26, 16, v26
	s_waitcnt lgkmcnt(0)
	v_lshlrev_b32_e32 v27, 16, v27
	v_mul_f32_e32 v27, v30, v27
	v_cvt_pk_bf16_f32 v27, v27, v27
	ds_write_b16 v47, v27 offset:4896
	v_max_f32_e64 v27, -v28, -v28
	v_exp_f32_e32 v26, v26
	v_min_f32_e32 v27, 0x42e60000, v27
	v_exp_f32_e32 v27, v27
	v_sub_f32_e32 v26, 1.0, v26
	v_mul_f32_e32 v27, v27, v26
	v_cvt_pk_bf16_f32 v27, v27, v27
	ds_write_b16 v47, v27 offset:13600
	v_sub_f32_e32 v27, v43, v28
	v_exp_f32_e32 v27, v27
	v_add_u32_e32 v28, v42, v103
	v_mul_f32_e32 v26, v27, v26
	v_cvt_pk_bf16_f32 v26, v26, v26
	ds_write_b16 v46, v26 offset:33408
	v_add_u32_e32 v26, v42, v102
	ds_read_u16 v27, v26 offset:17408
	ds_read_u16 v30, v28
	s_waitcnt lgkmcnt(1)
	v_lshlrev_b32_e32 v27, 16, v27
	s_waitcnt lgkmcnt(0)
	v_lshlrev_b32_e32 v30, 16, v30
	v_mul_f32_e32 v30, v31, v30
	v_cvt_pk_bf16_f32 v30, v30, v30
	ds_write_b16 v28, v30
	v_max_f32_e64 v30, -v29, -v29
	v_exp_f32_e32 v27, v27
	v_min_f32_e32 v30, 0x42e60000, v30
	v_exp_f32_e32 v30, v30
	v_sub_f32_e32 v27, 1.0, v27
	v_mul_f32_e32 v30, v30, v27
	v_cvt_pk_bf16_f32 v30, v30, v30
	ds_write_b16 v28, v30 offset:8704
	v_sub_f32_e32 v28, v43, v29
	v_exp_f32_e32 v28, v28
	s_nop 0
	v_mul_f32_e32 v27, v28, v27
	v_cvt_pk_bf16_f32 v27, v27, v27
	ds_write_b16 v26, v27 offset:27648
	s_and_saveexec_b64 s[22:23], s[0:1]
	s_cbranch_execz .LBB0_1328
	v_exp_f32_e32 v26, v43
	v_or_b32_e32 v27, s27, v77
	v_lshl_add_u32 v27, v27, 2, 0
	ds_write_b32 v27, v26 offset:56832

.LBB0_1331:
	s_and_b32 s22, s26, 1
	s_xor_b32 s20, s22, 1
	s_mul_i32 s20, s20, 0xe400
	s_add_i32 s28, s20, 0
	s_cmp_lg_u32 s26, 7
	s_cselect_b64 s[20:21], -1, 0
	s_cmp_eq_u32 s26, 7
	s_cbranch_scc1 .LBB0_1334
	v_add3_u32 v58, s28, v93, v80
	v_add3_u32 v59, s28, v94, v80
	s_cmp_gt_u32 s26, 5
	s_waitcnt vmcnt(3)
	ds_write_b128 v58, v[8:11]
	s_waitcnt vmcnt(2)
	ds_write_b128 v59, v[12:15] offset:17408
	s_waitcnt vmcnt(1)
	ds_write_b128 v59, v[18:21] offset:37888
	s_waitcnt vmcnt(0)
	ds_write_b128 v58, v[22:25] offset:48128
	s_cbranch_scc1 .LBB0_1334
	global_load_dwordx4 v[8:11], v[90:91], off offset:-2048 nt
	global_load_dwordx4 v[12:15], v[90:91], off offset:-1024 nt
	global_load_dwordx4 v[18:21], v[90:91], off nt
	global_load_dwordx4 v[22:25], v[90:91], off offset:1024 nt
